# P9 rows visited most-recently-written-first (FF from the down GEMM's last rounds still in the infinity cache) on top of v33
# baseline (speedup 1.0000x reference)
.LBB0_1014:
	s_or_b64 exec, exec, s[2:3]
	s_andn2_b64 vcc, exec, s[90:91]
	s_waitcnt lgkmcnt(0)
	s_barrier
	s_cbranch_vccnz .LBB0_1017
	global_load_dwordx4 v[0:3], v128, s[72:73]
	global_load_dwordx4 v[4:7], v128, s[72:73] offset:1024
	global_load_dwordx4 v[8:11], v128, s[72:73] offset:2048
	global_load_dwordx4 v[12:15], v128, s[72:73] offset:3072
	s_lshl_b32 s6, s86, 2
	s_lshl_b32 s8, s84, 5
	s_mov_b32 s98, 0
	s_mov_b32 s99, s6
.Lp9_cnt:
	s_add_i32 s98, s98, 1
	s_add_i32 s99, s99, s8
	s_cmp_lt_i32 s99, 0x10000
	s_cbranch_scc1 .Lp9_cnt
	s_cmp_eq_u32 s84, 0x100
	s_cbranch_scc0 .Lp9_keep
	s_lshr_b32 s99, s6, 10
	s_lshl_b32 s99, s99, 13
	s_and_b32 s6, s6, 0x3ff
	s_or_b32 s6, s6, s99
	s_or_b32 s6, s6, 0x1c00
	s_movk_i32 s8, 0xfc00
.Lp9_keep:
	s_ashr_i32 s7, s6, 31
	s_lshl_b64 s[0:1], s[6:7], 12
	s_add_u32 s0, s80, s0
	v_mov_b32_e32 v129, 0
	s_addc_u32 s1, s81, s1
	v_lshl_add_u64 v[16:17], s[0:1], 0, v[128:129]
	s_mov_b64 s[0:1], 0x3c00
	v_lshl_add_u64 v[48:49], v[16:17], 0, s[0:1]
	s_lshl_b64 s[0:1], s[6:7], 11
	s_ashr_i32 s9, s8, 31
	v_lshl_or_b32 v50, v144, 3, s0
	s_mov_b32 s0, 0x358637bd
	s_lshl_b64 s[10:11], s[8:9], 12
	v_mov_b32_e32 v51, s1
	s_lshl_b64 s[12:13], s[8:9], 11
	s_lshl_b64 s[14:15], s[6:7], 6
	s_lshl_b64 s[16:17], s[8:9], 6
	v_mov_b32_e32 v60, 0x9500000
	s_movk_i32 s7, 0xd000
	s_mov_b32 s18, 0x3a800000
	v_mov_b64_e32 v[52:53], s[0:1]
	s_mov_b32 s9, 0x800000
	s_movk_i32 s19, 0xe000
	s_movk_i32 s20, 0xf000
	s_movk_i32 s21, 0x1000
.LBB0_1016:
	v_add_co_u32_e32 v54, vcc, s7, v48
	s_add_u32 s0, s82, s14
	s_nop 0
	v_addc_co_u32_e32 v55, vcc, -1, v49, vcc
	v_add_co_u32_e32 v56, vcc, s19, v48
	v_lshl_add_u64 v[36:37], s[82:83], 0, v[50:51]
	s_nop 0
	v_addc_co_u32_e32 v57, vcc, -1, v49, vcc
	v_add_co_u32_e32 v58, vcc, s20, v48
	s_addc_u32 s1, s83, s15
	s_nop 0
	v_addc_co_u32_e32 v59, vcc, -1, v49, vcc
	v_add_co_u32_e32 v110, vcc, s21, v36
	s_add_u32 s2, s0, 0x9500000
	s_nop 0
	v_addc_co_u32_e32 v111, vcc, 0, v37, vcc
	s_addc_u32 s3, s1, 0
	global_load_dwordx4 v[16:19], v[48:49], off offset:-3072 nt
	global_load_dwordx4 v[20:23], v[48:49], off offset:-2048 nt
	global_load_dwordx4 v[24:27], v[48:49], off offset:-1024 nt
	global_load_dwordx4 v[28:31], v[48:49], off nt
	global_load_dwordx2 v[126:127], v[36:37], off nt
	global_load_dwordx2 v[162:163], v[36:37], off offset:512 nt
	global_load_dwordx2 v[164:165], v[36:37], off offset:1024 nt
	global_load_dwordx2 v[166:167], v[36:37], off offset:1536 nt
	global_load_dwordx4 v[62:65], v[54:55], off offset:-3072 nt
	global_load_dwordx4 v[66:69], v[54:55], off offset:-2048 nt
	global_load_dwordx4 v[70:73], v[56:57], off offset:-4096 nt
	global_load_dwordx4 v[74:77], v[56:57], off offset:-3072 nt
	global_load_dwordx2 v[168:169], v[36:37], off offset:2048 nt
	global_load_dwordx4 v[78:81], v[56:57], off offset:-2048 nt
	global_load_dwordx4 v[82:85], v[56:57], off offset:-1024 nt
	global_load_dwordx2 v[170:171], v[36:37], off offset:2560 nt
	global_load_dwordx2 v[172:173], v[36:37], off offset:3072 nt
	global_load_dwordx2 v[174:175], v[36:37], off offset:3584 nt
	global_load_dwordx4 v[86:89], v[54:55], off offset:-1024 nt
	global_load_dwordx4 v[32:35], v[58:59], off offset:-3072 nt
	global_load_dwordx4 v[44:47], v[58:59], off offset:-2048 nt
	s_nop 0
	global_load_dwordx4 v[36:39], v[58:59], off offset:-1024 nt
	global_load_dwordx4 v[90:93], v[56:57], off nt
	global_load_dwordx4 v[40:43], v[48:49], off offset:-4096 nt
	global_load_dwordx4 v[94:97], v60, s[0:1]
	global_load_dwordx4 v[98:101], v60, s[0:1] offset:64
	global_load_dwordx4 v[102:105], v60, s[0:1] offset:128
	global_load_dwordx4 v[106:109], v60, s[0:1] offset:192
	global_load_dwordx2 v[176:177], v[110:111], off nt
	global_load_dwordx2 v[178:179], v[110:111], off offset:512 nt
	global_load_dwordx2 v[180:181], v[110:111], off offset:1024 nt
	global_load_dwordx2 v[182:183], v[110:111], off offset:1536 nt
	global_load_dwordx2 v[184:185], v[110:111], off offset:2048 nt
	global_load_dwordx2 v[186:187], v[110:111], off offset:2560 nt
	global_load_dwordx2 v[188:189], v[110:111], off offset:3072 nt
	global_load_dwordx2 v[190:191], v[110:111], off offset:3584 nt
	s_nop 0
	global_load_dwordx4 v[110:113], v129, s[2:3] offset:48
	global_load_dwordx4 v[114:117], v129, s[2:3] offset:32
	global_load_dwordx4 v[118:121], v129, s[2:3] offset:16
	s_add_u32 s2, s0, 0x9500040
	s_addc_u32 s3, s1, 0
	global_load_dwordx4 v[122:125], v129, s[2:3] offset:48
	global_load_dwordx4 v[130:133], v129, s[2:3] offset:32
	global_load_dwordx4 v[134:137], v129, s[2:3] offset:16
	s_add_u32 s2, s0, 0x9500080
	s_addc_u32 s3, s1, 0
	global_load_dwordx4 v[138:141], v129, s[2:3] offset:48
	global_load_dwordx4 v[142:145], v129, s[2:3] offset:32
	global_load_dwordx4 v[146:149], v129, s[2:3] offset:16
	s_add_u32 s0, s0, 0x95000c0
	s_addc_u32 s1, s1, 0
	global_load_dwordx4 v[150:153], v129, s[0:1] offset:48
	global_load_dwordx4 v[154:157], v129, s[0:1] offset:32
	global_load_dwordx4 v[158:161], v129, s[0:1] offset:16
	s_add_i32 s6, s6, s8
	s_add_u32 s14, s14, s16
	s_addc_u32 s15, s15, s17
	v_lshl_add_u64 v[50:51], v[50:51], 0, s[12:13]
	s_sub_i32 s98, s98, 1
	s_cmp_gt_i32 s98, 0
	s_waitcnt vmcnt(40)
	v_lshlrev_b32_e32 v198, 16, v166
	v_and_b32_e32 v199, 0xffff0000, v166
	v_lshlrev_b32_e32 v166, 16, v167
	v_and_b32_e32 v167, 0xffff0000, v167
	s_waitcnt vmcnt(35)
	v_lshlrev_b32_e32 v200, 16, v168
	v_and_b32_e32 v201, 0xffff0000, v168
	v_lshlrev_b32_e32 v168, 16, v169
	s_waitcnt vmcnt(23)
	v_mov_b32_e32 v208, v95
	v_mov_b32_e32 v209, v96
	v_mov_b32_e32 v95, v97
	s_waitcnt vmcnt(22)
	v_mov_b32_e32 v96, v99
	v_mov_b32_e32 v97, v100
	v_mov_b32_e32 v99, v101
	s_waitcnt vmcnt(21)
	v_mov_b32_e32 v100, v103
	v_mov_b32_e32 v101, v104
	v_mov_b32_e32 v103, v105
	s_waitcnt vmcnt(20)
	v_mov_b32_e32 v104, v107
	v_mov_b32_e32 v105, v108
	v_mov_b32_e32 v107, v109
	v_pk_add_f32 v[96:97], v[96:97], v[98:99]
	v_pk_add_f32 v[98:99], v[100:101], v[102:103]
	s_waitcnt vmcnt(9)
	v_mov_b32_e32 v102, v119
	v_mov_b32_e32 v103, v120
	v_mov_b32_e32 v119, v121
	v_pk_add_f32 v[94:95], v[208:209], v[94:95]
	v_pk_add_f32 v[100:101], v[104:105], v[106:107]
	v_add_f32_e32 v104, v114, v115
	v_add_f32_e32 v106, v116, v117
	v_mov_b32_e32 v105, v112
	v_mov_b32_e32 v107, v113
	v_pk_add_f32 v[102:103], v[102:103], v[118:119]
	v_pk_add_f32 v[94:95], v[94:95], v[94:95] op_sel:[0,1] op_sel_hi:[1,0]
	v_pk_add_f32 v[104:105], v[104:105], v[106:107]
	v_pk_add_f32 v[102:103], v[102:103], v[102:103] op_sel:[0,1] op_sel_hi:[1,0]
	s_waitcnt vmcnt(6)
	v_mov_b32_e32 v106, v135
	v_mov_b32_e32 v107, v136
	v_mov_b32_e32 v135, v137
	v_mov_b32_e32 v95, v110
	v_mov_b32_e32 v103, v111
	v_pk_add_f32 v[106:107], v[106:107], v[134:135]
	v_pk_add_f32 v[96:97], v[96:97], v[96:97] op_sel:[0,1] op_sel_hi:[1,0]
	v_add_f32_e32 v112, v130, v131
	v_add_f32_e32 v114, v132, v133
	v_mov_b32_e32 v113, v124
	v_mov_b32_e32 v115, v125
	v_pk_add_f32 v[94:95], v[94:95], v[102:103]
	v_pk_add_f32 v[102:103], v[106:107], v[106:107] op_sel:[0,1] op_sel_hi:[1,0]
	s_waitcnt vmcnt(3)
	v_mov_b32_e32 v106, v147
	v_mov_b32_e32 v107, v148
	v_mov_b32_e32 v147, v149
	v_mov_b32_e32 v97, v122
	v_pk_add_f32 v[110:111], v[112:113], v[114:115]
	v_add_f32_e32 v112, v142, v143
	v_add_f32_e32 v114, v144, v145
	v_mov_b32_e32 v113, v140
	v_mov_b32_e32 v115, v141
	v_pk_add_f32 v[94:95], v[94:95], v[104:105]
	v_mov_b32_e32 v103, v123
	v_pk_add_f32 v[104:105], v[106:107], v[146:147]
	v_pk_add_f32 v[98:99], v[98:99], v[98:99] op_sel:[0,1] op_sel_hi:[1,0]
	v_pk_add_f32 v[106:107], v[112:113], v[114:115]
	v_pk_add_f32 v[96:97], v[96:97], v[102:103]
	v_pk_add_f32 v[104:105], v[104:105], v[104:105] op_sel:[0,1] op_sel_hi:[1,0]
	s_waitcnt vmcnt(0)
	v_mov_b32_e32 v112, v159
	v_mov_b32_e32 v113, v160
	v_mov_b32_e32 v159, v161
	v_mov_b32_e32 v99, v138
	v_pk_add_f32 v[96:97], v[96:97], v[110:111]
	v_mov_b32_e32 v105, v139
	v_pk_add_f32 v[110:111], v[112:113], v[158:159]
	v_pk_add_f32 v[100:101], v[100:101], v[100:101] op_sel:[0,1] op_sel_hi:[1,0]
	v_mov_b32_e32 v103, v94
	v_mov_b32_e32 v102, v96
	v_mov_b32_e32 v94, v97
	v_pk_add_f32 v[96:97], v[98:99], v[104:105]
	v_pk_add_f32 v[98:99], v[110:111], v[110:111] op_sel:[0,1] op_sel_hi:[1,0]
	v_add_f32_e32 v114, v154, v155
	v_add_f32_e32 v116, v156, v157
	v_mov_b32_e32 v101, v150
	v_mov_b32_e32 v115, v152
	v_mov_b32_e32 v117, v153
	v_pk_add_f32 v[94:95], v[102:103], v[94:95]
	v_mov_b32_e32 v99, v151
	v_pk_add_f32 v[112:113], v[114:115], v[116:117]
	v_pk_add_f32 v[96:97], v[96:97], v[106:107]
	v_pk_fma_f32 v[94:95], v[94:95], s[18:19], v[52:53] op_sel_hi:[1,0,0]
	v_pk_add_f32 v[98:99], v[100:101], v[98:99]
	v_mov_b32_e32 v101, v96
	v_mul_f32_e32 v96, 0x4b800000, v94
	v_cmp_gt_f32_e32 vcc, s9, v94
	v_pk_add_f32 v[98:99], v[98:99], v[112:113]
	v_mul_f32_e32 v61, 0x4b800000, v95
	v_cmp_gt_f32_e64 s[0:1], s9, v95
	v_cndmask_b32_e32 v94, v94, v96, vcc
	v_mov_b32_e32 v100, v98
	v_mov_b32_e32 v96, v99
	v_cndmask_b32_e64 v61, v95, v61, s[0:1]
	v_rsq_f32_e32 v98, v94
	v_pk_add_f32 v[94:95], v[100:101], v[96:97]
	v_rsq_f32_e32 v61, v61
	v_pk_fma_f32 v[94:95], v[94:95], s[18:19], v[52:53] op_sel_hi:[1,0,0]
	v_lshlrev_b32_e32 v192, 16, v126
	v_mul_f32_e32 v96, 0x4b800000, v95
	v_cmp_gt_f32_e64 s[4:5], s9, v95
	v_mul_f32_e32 v97, 0x4b800000, v94
	v_cmp_gt_f32_e64 s[2:3], s9, v94
	v_cndmask_b32_e64 v95, v95, v96, s[4:5]
	v_rsq_f32_e32 v128, v95
	v_cndmask_b32_e64 v94, v94, v97, s[2:3]
	v_mul_f32_e32 v96, 0x45800000, v61
	v_rsq_f32_e32 v130, v94
	v_and_b32_e32 v193, 0xffff0000, v126
	v_lshlrev_b32_e32 v126, 16, v127
	v_and_b32_e32 v127, 0xffff0000, v127
	v_mul_f32_e32 v97, 0x45800000, v98
	v_cndmask_b32_e64 v94, v61, v96, s[0:1]
	v_lshlrev_b32_e32 v194, 16, v162
	v_and_b32_e32 v195, 0xffff0000, v162
	v_lshlrev_b32_e32 v162, 16, v163
	v_and_b32_e32 v163, 0xffff0000, v163
	v_lshlrev_b32_e32 v196, 16, v164
	v_and_b32_e32 v197, 0xffff0000, v164
	v_lshlrev_b32_e32 v164, 16, v165
	v_and_b32_e32 v165, 0xffff0000, v165
	v_and_b32_e32 v169, 0xffff0000, v169
	v_lshlrev_b32_e32 v202, 16, v170
	v_and_b32_e32 v203, 0xffff0000, v170
	v_lshlrev_b32_e32 v170, 16, v171
	v_and_b32_e32 v171, 0xffff0000, v171
	v_lshlrev_b32_e32 v204, 16, v172
	v_and_b32_e32 v205, 0xffff0000, v172
	v_lshlrev_b32_e32 v172, 16, v173
	v_and_b32_e32 v173, 0xffff0000, v173
	v_lshlrev_b32_e32 v206, 16, v174
	v_and_b32_e32 v207, 0xffff0000, v174
	v_lshlrev_b32_e32 v174, 16, v175
	v_and_b32_e32 v175, 0xffff0000, v175
	v_cndmask_b32_e32 v96, v98, v97, vcc
	v_pk_mul_f32 v[98:99], v[94:95], v[192:193] op_sel_hi:[0,1]
	v_pk_mul_f32 v[100:101], v[94:95], v[126:127] op_sel_hi:[0,1]
	v_pk_mul_f32 v[102:103], v[94:95], v[194:195] op_sel_hi:[0,1]
	v_pk_mul_f32 v[104:105], v[94:95], v[162:163] op_sel_hi:[0,1]
	v_pk_mul_f32 v[106:107], v[94:95], v[196:197] op_sel_hi:[0,1]
	v_pk_mul_f32 v[110:111], v[94:95], v[164:165] op_sel_hi:[0,1]
	v_pk_mul_f32 v[112:113], v[94:95], v[198:199] op_sel_hi:[0,1]
	v_pk_mul_f32 v[94:95], v[94:95], v[166:167] op_sel_hi:[0,1]
	v_pk_mul_f32 v[114:115], v[96:97], v[200:201] op_sel_hi:[0,1]
	v_pk_mul_f32 v[116:117], v[96:97], v[168:169] op_sel_hi:[0,1]
	v_pk_mul_f32 v[118:119], v[96:97], v[202:203] op_sel_hi:[0,1]
	v_pk_mul_f32 v[120:121], v[96:97], v[170:171] op_sel_hi:[0,1]
	v_pk_mul_f32 v[122:123], v[96:97], v[204:205] op_sel_hi:[0,1]
	v_pk_mul_f32 v[124:125], v[96:97], v[172:173] op_sel_hi:[0,1]
	v_pk_mul_f32 v[126:127], v[96:97], v[206:207] op_sel_hi:[0,1]
	v_pk_mul_f32 v[96:97], v[96:97], v[174:175] op_sel_hi:[0,1]
	v_pk_fma_f32 v[64:65], v[2:3], v[100:101], v[64:65]
	v_pk_fma_f32 v[62:63], v[0:1], v[98:99], v[62:63]
	v_mul_f32_e32 v61, 0x45800000, v128
	v_lshlrev_b32_e32 v108, 16, v176
	v_and_b32_e32 v109, 0xffff0000, v176
	v_lshlrev_b32_e32 v176, 16, v177
	v_and_b32_e32 v177, 0xffff0000, v177
	v_pk_fma_f32 v[68:69], v[6:7], v[104:105], v[68:69]
	v_pk_fma_f32 v[66:67], v[4:5], v[102:103], v[66:67]
	v_pk_fma_f32 v[88:89], v[10:11], v[110:111], v[88:89]
	v_pk_fma_f32 v[86:87], v[8:9], v[106:107], v[86:87]
	v_pk_fma_f32 v[72:73], v[14:15], v[94:95], v[72:73]
	v_pk_fma_f32 v[70:71], v[12:13], v[112:113], v[70:71]
	v_pk_fma_f32 v[76:77], v[2:3], v[116:117], v[76:77]
	v_pk_fma_f32 v[74:75], v[0:1], v[114:115], v[74:75]
	v_pk_fma_f32 v[80:81], v[6:7], v[120:121], v[80:81]
	v_pk_fma_f32 v[78:79], v[4:5], v[118:119], v[78:79]
	v_pk_fma_f32 v[84:85], v[10:11], v[124:125], v[84:85]
	v_pk_fma_f32 v[82:83], v[8:9], v[122:123], v[82:83]
	v_pk_fma_f32 v[92:93], v[14:15], v[96:97], v[92:93]
	v_pk_fma_f32 v[90:91], v[12:13], v[126:127], v[90:91]
	v_mul_f32_e32 v94, 0x45800000, v130
	global_store_dwordx4 v[54:55], v[62:65], off offset:-3072 nt
	global_store_dwordx4 v[54:55], v[66:69], off offset:-2048 nt
	global_store_dwordx4 v[54:55], v[86:89], off offset:-1024 nt
	global_store_dwordx4 v[56:57], v[70:73], off offset:-4096 nt
	global_store_dwordx4 v[56:57], v[74:77], off offset:-3072 nt
	global_store_dwordx4 v[56:57], v[78:81], off offset:-2048 nt
	global_store_dwordx4 v[56:57], v[82:85], off offset:-1024 nt
	global_store_dwordx4 v[56:57], v[90:93], off nt
	v_cndmask_b32_e64 v54, v128, v61, s[4:5]
	v_lshlrev_b32_e32 v210, 16, v178
	v_and_b32_e32 v211, 0xffff0000, v178
	v_lshlrev_b32_e32 v178, 16, v179
	v_and_b32_e32 v179, 0xffff0000, v179
	v_lshlrev_b32_e32 v212, 16, v180
	v_and_b32_e32 v213, 0xffff0000, v180
	v_lshlrev_b32_e32 v180, 16, v181
	v_and_b32_e32 v181, 0xffff0000, v181
	v_lshlrev_b32_e32 v214, 16, v182
	v_and_b32_e32 v215, 0xffff0000, v182
	v_lshlrev_b32_e32 v182, 16, v183
	v_and_b32_e32 v183, 0xffff0000, v183
	v_lshlrev_b32_e32 v216, 16, v184
	v_and_b32_e32 v217, 0xffff0000, v184
	v_lshlrev_b32_e32 v184, 16, v185
	v_and_b32_e32 v185, 0xffff0000, v185
	v_lshlrev_b32_e32 v218, 16, v186
	v_and_b32_e32 v219, 0xffff0000, v186
	v_lshlrev_b32_e32 v186, 16, v187
	v_and_b32_e32 v187, 0xffff0000, v187
	v_lshlrev_b32_e32 v220, 16, v188
	v_and_b32_e32 v221, 0xffff0000, v188
	v_lshlrev_b32_e32 v188, 16, v189
	v_and_b32_e32 v189, 0xffff0000, v189
	v_lshlrev_b32_e32 v222, 16, v190
	v_and_b32_e32 v223, 0xffff0000, v190
	v_lshlrev_b32_e32 v190, 16, v191
	v_and_b32_e32 v191, 0xffff0000, v191
	v_cndmask_b32_e64 v56, v130, v94, s[2:3]
	v_pk_mul_f32 v[62:63], v[54:55], v[108:109] op_sel_hi:[0,1]
	v_pk_mul_f32 v[64:65], v[54:55], v[176:177] op_sel_hi:[0,1]
	v_pk_mul_f32 v[66:67], v[54:55], v[210:211] op_sel_hi:[0,1]
	v_pk_mul_f32 v[68:69], v[54:55], v[178:179] op_sel_hi:[0,1]
	v_pk_mul_f32 v[70:71], v[54:55], v[212:213] op_sel_hi:[0,1]
	v_pk_mul_f32 v[72:73], v[54:55], v[180:181] op_sel_hi:[0,1]
	v_pk_mul_f32 v[74:75], v[54:55], v[214:215] op_sel_hi:[0,1]
	v_pk_mul_f32 v[54:55], v[54:55], v[182:183] op_sel_hi:[0,1]
	v_pk_mul_f32 v[76:77], v[56:57], v[216:217] op_sel_hi:[0,1]
	v_pk_mul_f32 v[78:79], v[56:57], v[184:185] op_sel_hi:[0,1]
	v_pk_mul_f32 v[80:81], v[56:57], v[218:219] op_sel_hi:[0,1]
	v_pk_mul_f32 v[82:83], v[56:57], v[186:187] op_sel_hi:[0,1]
	v_pk_mul_f32 v[84:85], v[56:57], v[220:221] op_sel_hi:[0,1]
	v_pk_mul_f32 v[86:87], v[56:57], v[188:189] op_sel_hi:[0,1]
	v_pk_mul_f32 v[88:89], v[56:57], v[222:223] op_sel_hi:[0,1]
	v_pk_mul_f32 v[56:57], v[56:57], v[190:191] op_sel_hi:[0,1]
	v_pk_fma_f32 v[34:35], v[2:3], v[64:65], v[34:35]
	v_pk_fma_f32 v[32:33], v[0:1], v[62:63], v[32:33]
	v_pk_fma_f32 v[46:47], v[6:7], v[68:69], v[46:47]
	v_pk_fma_f32 v[44:45], v[4:5], v[66:67], v[44:45]
	v_pk_fma_f32 v[38:39], v[10:11], v[72:73], v[38:39]
	v_pk_fma_f32 v[36:37], v[8:9], v[70:71], v[36:37]
	v_pk_fma_f32 v[42:43], v[14:15], v[54:55], v[42:43]
	v_pk_fma_f32 v[40:41], v[12:13], v[74:75], v[40:41]
	v_pk_fma_f32 v[18:19], v[2:3], v[78:79], v[18:19]
	v_pk_fma_f32 v[16:17], v[0:1], v[76:77], v[16:17]
	v_pk_fma_f32 v[22:23], v[6:7], v[82:83], v[22:23]
	v_pk_fma_f32 v[20:21], v[4:5], v[80:81], v[20:21]
	v_pk_fma_f32 v[26:27], v[10:11], v[86:87], v[26:27]
	v_pk_fma_f32 v[24:25], v[8:9], v[84:85], v[24:25]
	v_pk_fma_f32 v[30:31], v[14:15], v[56:57], v[30:31]
	v_pk_fma_f32 v[28:29], v[12:13], v[88:89], v[28:29]
	global_store_dwordx4 v[58:59], v[32:35], off offset:-3072 nt
	global_store_dwordx4 v[58:59], v[44:47], off offset:-2048 nt
	global_store_dwordx4 v[58:59], v[36:39], off offset:-1024 nt
	global_store_dwordx4 v[48:49], v[40:43], off offset:-4096 nt
	global_store_dwordx4 v[48:49], v[16:19], off offset:-3072 nt
	global_store_dwordx4 v[48:49], v[20:23], off offset:-2048 nt
	global_store_dwordx4 v[48:49], v[24:27], off offset:-1024 nt
	global_store_dwordx4 v[48:49], v[28:31], off nt
	v_lshl_add_u64 v[48:49], v[48:49], 0, s[10:11]
	s_cbranch_scc1 .LBB0_1016
